# v35 + W_up layer-1 conversion moved to the idle workgroups of ML-in round 4
# speedup vs baseline: 1.0183x; 1.0030x over previous
.LBB0_160:
	s_cmp_eq_u32 s101, 1
	s_cbranch_scc1 .Lcv1_ret
	s_cmp_eq_u32 s101, 4
	s_cbranch_scc1 .Lcv_relay_ret3
	s_cmp_lg_u32 s101, 0
	s_cbranch_scc1 .Lcv_relay_ret
	s_mov_b64 s[76:77], s[88:89]
	v_and_b32_e32 v20, 63, v0
	s_cmpk_gt_i32 s2, 0x407f
	v_mbcnt_lo_u32_b32 v166, -1, 0
	s_mov_b32 s72, s86
	s_mov_b64 s[78:79], s[90:91]
	s_cbranch_scc1 .LBB0_165
	v_mbcnt_hi_u32_b32 v4, -1, v166
	v_and_b32_e32 v5, 64, v4
	v_add_u32_e32 v5, 64, v5
	v_xor_b32_e32 v6, 1, v4
	v_cmp_lt_i32_e32 vcc, v6, v5
	s_load_dwordx2 s[4:5], s[0:1], 0x48
	v_mov_b32_e32 v3, 0
	v_cndmask_b32_e32 v6, v4, v6, vcc
	v_lshlrev_b32_e32 v19, 2, v6
	v_xor_b32_e32 v6, 2, v4
	v_cmp_lt_i32_e32 vcc, v6, v5
	v_lshlrev_b32_e32 v2, 4, v20
	s_waitcnt lgkmcnt(0)
	v_lshl_add_u64 v[22:23], s[4:5], 0, v[2:3]
	v_cndmask_b32_e32 v6, v4, v6, vcc
	v_lshlrev_b32_e32 v32, 2, v6
	v_xor_b32_e32 v6, 4, v4
	v_cmp_lt_i32_e32 vcc, v6, v5
	s_mov_b64 s[4:5], 0x4200000
	v_lshl_add_u64 v[26:27], s[76:77], 0, v[2:3]
	v_cndmask_b32_e32 v6, v4, v6, vcc
	v_lshlrev_b32_e32 v33, 2, v6
	v_xor_b32_e32 v6, 8, v4
	v_cmp_lt_i32_e32 vcc, v6, v5
	v_lshlrev_b32_e32 v37, 4, v20
	v_mov_b32_e32 v38, 0x358637bd
	v_cndmask_b32_e32 v6, v4, v6, vcc
	v_lshlrev_b32_e32 v34, 2, v6
	v_xor_b32_e32 v6, 16, v4
	v_cmp_lt_i32_e32 vcc, v6, v5
	s_mov_b32 s3, 0xf800000
	v_mov_b32_e32 v39, 0x260
	v_cndmask_b32_e32 v6, v4, v6, vcc
	v_lshlrev_b32_e32 v35, 2, v6
	v_xor_b32_e32 v6, 32, v4
	v_cmp_lt_i32_e32 vcc, v6, v5
	v_mov_b32_e32 v5, v3
	s_nop 0
	v_cndmask_b32_e32 v4, v4, v6, vcc
	v_lshlrev_b32_e32 v36, 2, v4
	v_lshlrev_b32_e32 v4, 3, v20
	v_lshl_add_u64 v[4:5], s[78:79], 0, v[4:5]
	v_lshl_add_u64 v[24:25], v[4:5], 0, s[4:5]
	s_mov_b32 s4, s2
	s_branch .LBB0_163

.LBB0_1465:
	s_waitcnt vmcnt(0)
	s_barrier
	v_readlane_b32 s101, v254, 19
	s_cmpk_lt_u32 s101, 77
	s_cbranch_scc1 .Lcv3_skip
	v_writelane_b32 v200, s2, 0
	v_writelane_b32 v200, s3, 1
	v_writelane_b32 v200, s4, 2
	v_writelane_b32 v200, s5, 3
	v_writelane_b32 v200, s6, 4
	v_writelane_b32 v200, s7, 5
	v_writelane_b32 v200, s8, 6
	v_writelane_b32 v200, s9, 7
	v_writelane_b32 v200, s10, 8
	v_writelane_b32 v200, s11, 9
	v_writelane_b32 v200, s12, 10
	v_writelane_b32 v200, s13, 11
	v_writelane_b32 v200, s14, 12
	v_writelane_b32 v200, s15, 13
	v_writelane_b32 v200, s16, 14
	v_writelane_b32 v200, s17, 15
	v_writelane_b32 v200, s18, 16
	v_writelane_b32 v200, s19, 17
	v_writelane_b32 v200, s20, 18
	v_writelane_b32 v200, s21, 19
	v_writelane_b32 v200, s22, 20
	v_writelane_b32 v200, s23, 21
	v_writelane_b32 v200, s24, 22
	v_writelane_b32 v200, s25, 23
	v_writelane_b32 v200, s26, 24
	v_writelane_b32 v200, s27, 25
	v_writelane_b32 v200, s28, 26
	v_writelane_b32 v200, s29, 27
	v_writelane_b32 v200, s30, 28
	v_writelane_b32 v200, s31, 29
	v_writelane_b32 v200, s32, 30
	v_writelane_b32 v200, s33, 31
	v_writelane_b32 v200, s34, 32
	v_writelane_b32 v200, s35, 33
	v_writelane_b32 v200, s36, 34
	v_writelane_b32 v200, s37, 35
	v_writelane_b32 v200, s38, 36
	v_writelane_b32 v200, s39, 37
	v_writelane_b32 v200, s40, 38
	v_writelane_b32 v200, s41, 39
	v_writelane_b32 v200, s42, 40
	v_writelane_b32 v200, s43, 41
	v_writelane_b32 v200, s44, 42
	v_writelane_b32 v200, s45, 43
	v_writelane_b32 v200, s46, 44
	v_writelane_b32 v200, s47, 45
	v_writelane_b32 v200, s48, 46
	v_writelane_b32 v200, s49, 47
	v_writelane_b32 v200, s50, 48
	v_writelane_b32 v200, s51, 49
	v_writelane_b32 v200, s52, 50
	v_writelane_b32 v200, s53, 51
	v_writelane_b32 v200, s54, 52
	v_writelane_b32 v200, s55, 53
	v_writelane_b32 v200, s56, 54
	v_writelane_b32 v200, s57, 55
	v_writelane_b32 v200, s58, 56
	v_writelane_b32 v200, s59, 57
	v_writelane_b32 v200, s60, 58
	v_writelane_b32 v200, s61, 59
	v_writelane_b32 v200, s62, 60
	v_writelane_b32 v200, s63, 61
	v_writelane_b32 v200, s64, 62
	v_writelane_b32 v200, s65, 63
	v_writelane_b32 v201, s66, 0
	v_writelane_b32 v201, s67, 1
	v_writelane_b32 v201, s68, 2
	v_writelane_b32 v201, s69, 3
	v_writelane_b32 v201, s70, 4
	v_writelane_b32 v201, s71, 5
	v_writelane_b32 v201, s72, 6
	v_writelane_b32 v201, s73, 7
	v_writelane_b32 v201, s74, 8
	v_writelane_b32 v201, s75, 9
	v_writelane_b32 v201, s76, 10
	v_writelane_b32 v201, s77, 11
	v_writelane_b32 v201, s78, 12
	v_writelane_b32 v201, s79, 13
	v_writelane_b32 v201, s80, 14
	v_writelane_b32 v201, s81, 15
	v_writelane_b32 v201, s82, 16
	v_writelane_b32 v201, s83, 17
	v_writelane_b32 v201, s84, 18
	v_writelane_b32 v201, s85, 19
	v_writelane_b32 v201, s86, 20
	v_writelane_b32 v201, s87, 21
	v_writelane_b32 v201, s88, 22
	v_writelane_b32 v201, s89, 23
	v_writelane_b32 v201, s90, 24
	v_writelane_b32 v201, s91, 25
	v_writelane_b32 v201, s92, 26
	v_writelane_b32 v201, s93, 27
	v_writelane_b32 v201, s94, 28
	v_writelane_b32 v201, s95, 29
	v_writelane_b32 v201, s96, 30
	v_writelane_b32 v201, s97, 31
	v_writelane_b32 v201, s98, 32
	v_writelane_b32 v201, s99, 33
	s_load_dwordx4 s[88:91], s[0:1], 0xb8
	v_mbcnt_lo_u32_b32 v0, -1, 0
	v_mbcnt_hi_u32_b32 v0, -1, v0
	v_readlane_b32 s87, v255, 4
	s_waitcnt lgkmcnt(0)
	v_and_b32_e32 v21, 31, v0
	v_bfe_u32 v31, v0, 5, 1
	v_lshlrev_b32_e32 v2, 2, v21
	v_mul_u32_u24_e32 v3, 0x84, v31
	v_bfe_u32 v29, v0, 3, 3
	s_lshl_b32 s2, s87, 14
	s_add_i32 s3, s2, 0
	v_add3_u32 v28, s3, v2, v3
	v_lshlrev_b32_e32 v2, 3, v0
	v_and_b32_e32 v2, 56, v2
	v_mul_u32_u24_e32 v4, 0x84, v2
	v_lshlrev_b32_e32 v5, 2, v29
	s_mov_b32 s7, 0
	v_mov_b32_e32 v3, 0
	v_add3_u32 v30, s3, v4, v5
	v_lshlrev_b32_e32 v18, 1, v2
	s_sub_i32 s2, s101, 77
	s_lshl_b32 s2, s2, 3
	s_add_i32 s2, s2, s87
	s_addk_i32 s2, 0x2000
	s_movk_i32 s43, 0x598
	s_movk_i32 s100, 0x2fff
	s_mov_b32 s101, 4
	s_branch .Lcv_relay_fwd

.Lcv3_skip:
	s_waitcnt vmcnt(0)
	v_readlane_b32 s2, v254, 6
	v_readlane_b32 s3, v254, 7
	s_and_b64 vcc, exec, s[2:3]
	s_barrier
	s_cbranch_vccz .LBB0_1511
	s_mov_b32 s2, -1
	s_nop 0
	v_mbcnt_lo_u32_b32 v0, s2, 0
	v_mbcnt_hi_u32_b32 v0, s2, v0
	v_cmp_eq_u32_e32 vcc, 0, v0
	s_and_saveexec_b64 s[36:37], vcc
	s_cbranch_execz .LBB0_1510
	v_readlane_b32 s56, v254, 4
	v_readlane_b32 s3, v255, 39
	s_mov_b32 s2, s83
	v_readlane_b32 s57, v254, 5
	v_mov_b32_e32 v0, s3
	s_waitcnt vmcnt(0) expcnt(0) lgkmcnt(0)
	ds_read_b32 v2, v0
	v_readlane_b32 s3, v255, 40
	s_waitcnt lgkmcnt(0)
	v_cmp_ne_u32_e32 vcc, 0, v2
	v_mov_b32_e32 v0, s3
	ds_read_b32 v0, v0
	s_cbranch_vccnz .LBB0_1481
	v_readlane_b32 s4, v254, 0
	v_readlane_b32 s5, v254, 1
	s_load_dwordx2 s[8:9], s[4:5], 0x4
	s_add_u32 s4, s56, 0x1000
	s_addc_u32 s5, s57, 0
	s_add_u32 s6, s56, 0x1100
	s_addc_u32 s7, s57, 0
	s_waitcnt lgkmcnt(0)
	s_mul_i32 s3, s8, s38
	s_add_u32 s8, s56, 0x1200
	s_mul_i32 s3, s3, s9
	s_addc_u32 s9, s57, 0
	s_add_u32 s10, s56, 0x1300
	s_addc_u32 s11, s57, 0
	s_mov_b32 s30, 1
	s_mov_b64 s[12:13], 0
	s_branch .LBB0_1471

.LBB0_2040:
	s_waitcnt vmcnt(0)
	s_barrier
	v_readlane_b32 s100, v254, 43
	v_readlane_b32 s101, v254, 19
	s_cmp_lg_u32 s100, 0
	s_cbranch_scc1 .Lwd_entry
	s_cmpk_lt_u32 s101, 32
	s_cbranch_scc1 .Lcv2_skip
	v_writelane_b32 v200, s2, 0
	v_writelane_b32 v200, s3, 1
	v_writelane_b32 v200, s4, 2
	v_writelane_b32 v200, s5, 3
	v_writelane_b32 v200, s6, 4
	v_writelane_b32 v200, s7, 5
	v_writelane_b32 v200, s8, 6
	v_writelane_b32 v200, s9, 7
	v_writelane_b32 v200, s10, 8
	v_writelane_b32 v200, s11, 9
	v_writelane_b32 v200, s12, 10
	v_writelane_b32 v200, s13, 11
	v_writelane_b32 v200, s14, 12
	v_writelane_b32 v200, s15, 13
	v_writelane_b32 v200, s16, 14
	v_writelane_b32 v200, s17, 15
	v_writelane_b32 v200, s18, 16
	v_writelane_b32 v200, s19, 17
	v_writelane_b32 v200, s20, 18
	v_writelane_b32 v200, s21, 19
	v_writelane_b32 v200, s22, 20
	v_writelane_b32 v200, s23, 21
	v_writelane_b32 v200, s24, 22
	v_writelane_b32 v200, s25, 23
	v_writelane_b32 v200, s26, 24
	v_writelane_b32 v200, s27, 25
	v_writelane_b32 v200, s28, 26
	v_writelane_b32 v200, s29, 27
	v_writelane_b32 v200, s30, 28
	v_writelane_b32 v200, s31, 29
	v_writelane_b32 v200, s32, 30
	v_writelane_b32 v200, s33, 31
	v_writelane_b32 v200, s34, 32
	v_writelane_b32 v200, s35, 33
	v_writelane_b32 v200, s36, 34
	v_writelane_b32 v200, s37, 35
	v_writelane_b32 v200, s38, 36
	v_writelane_b32 v200, s39, 37
	v_writelane_b32 v200, s40, 38
	v_writelane_b32 v200, s41, 39
	v_writelane_b32 v200, s42, 40
	v_writelane_b32 v200, s43, 41
	v_writelane_b32 v200, s44, 42
	v_writelane_b32 v200, s45, 43
	v_writelane_b32 v200, s46, 44
	v_writelane_b32 v200, s47, 45
	v_writelane_b32 v200, s48, 46
	v_writelane_b32 v200, s49, 47
	v_writelane_b32 v200, s50, 48
	v_writelane_b32 v200, s51, 49
	v_writelane_b32 v200, s52, 50
	v_writelane_b32 v200, s53, 51
	v_writelane_b32 v200, s54, 52
	v_writelane_b32 v200, s55, 53
	v_writelane_b32 v200, s56, 54
	v_writelane_b32 v200, s57, 55
	v_writelane_b32 v200, s58, 56
	v_writelane_b32 v200, s59, 57
	v_writelane_b32 v200, s60, 58
	v_writelane_b32 v200, s61, 59
	v_writelane_b32 v200, s62, 60
	v_writelane_b32 v200, s63, 61
	v_writelane_b32 v200, s64, 62
	v_writelane_b32 v200, s65, 63
	v_writelane_b32 v201, s66, 0
	v_writelane_b32 v201, s67, 1
	v_writelane_b32 v201, s68, 2
	v_writelane_b32 v201, s69, 3
	v_writelane_b32 v201, s70, 4
	v_writelane_b32 v201, s71, 5
	v_writelane_b32 v201, s72, 6
	v_writelane_b32 v201, s73, 7
	v_writelane_b32 v201, s74, 8
	v_writelane_b32 v201, s75, 9
	v_writelane_b32 v201, s76, 10
	v_writelane_b32 v201, s77, 11
	v_writelane_b32 v201, s78, 12
	v_writelane_b32 v201, s79, 13
	v_writelane_b32 v201, s80, 14
	v_writelane_b32 v201, s81, 15
	v_writelane_b32 v201, s82, 16
	v_writelane_b32 v201, s83, 17
	v_writelane_b32 v201, s84, 18
	v_writelane_b32 v201, s85, 19
	v_writelane_b32 v201, s86, 20
	v_writelane_b32 v201, s87, 21
	v_writelane_b32 v201, s88, 22
	v_writelane_b32 v201, s89, 23
	v_writelane_b32 v201, s90, 24
	v_writelane_b32 v201, s91, 25
	v_writelane_b32 v201, s92, 26
	v_writelane_b32 v201, s93, 27
	v_writelane_b32 v201, s94, 28
	v_writelane_b32 v201, s95, 29
	v_writelane_b32 v201, s96, 30
	v_writelane_b32 v201, s97, 31
	v_writelane_b32 v201, s98, 32
	v_writelane_b32 v201, s99, 33
	s_load_dwordx4 s[88:91], s[0:1], 0xb8
	v_mbcnt_lo_u32_b32 v0, -1, 0
	v_mbcnt_hi_u32_b32 v0, -1, v0
	v_readlane_b32 s87, v255, 4
	s_waitcnt lgkmcnt(0)
	v_and_b32_e32 v21, 31, v0
	v_bfe_u32 v31, v0, 5, 1
	v_lshlrev_b32_e32 v2, 2, v21
	v_mul_u32_u24_e32 v3, 0x84, v31
	v_bfe_u32 v29, v0, 3, 3
	s_lshl_b32 s2, s87, 14
	s_add_i32 s3, s2, 0
	v_add3_u32 v28, s3, v2, v3
	v_lshlrev_b32_e32 v2, 3, v0
	v_and_b32_e32 v2, 56, v2
	v_mul_u32_u24_e32 v4, 0x84, v2
	v_lshlrev_b32_e32 v5, 2, v29
	s_mov_b32 s7, 0
	v_mov_b32_e32 v3, 0
	v_add3_u32 v30, s3, v4, v5
	v_lshlrev_b32_e32 v18, 1, v2
	s_sub_i32 s2, s101, 32
	s_lshl_b32 s2, s2, 3
	s_add_i32 s2, s2, s87
	s_addk_i32 s2, 0x3000
	s_movk_i32 s43, 0x700
	s_movk_i32 s100, 0x3fff
	s_mov_b32 s101, 2
	s_branch .Lcv_relay_fwd
